# kmat phase rewritten: branch-free masks, per-thread invariants hoisted, 9 loads in flight per g with next-g prefetch, saddr addressing
# speedup vs baseline: 1.0044x; 1.0022x over previous
; __device__ __forceinline__ int otid() { int t = threadIdx.x; asm volatile("" : "+v"(t)); return t; }
; __device__ __forceinline__ int obid() { int t = blockIdx.x; asm volatile("" : "+s"(t)); return t; }
; __device__ __forceinline__ unsigned pack2(float lo, float hi) { const f32x2_t v = {lo, hi}; const bf16x2_t b = __builtin_convertvector(v, bf16x2_t); return __builtin_bit_cast(unsigned, b); }
; __device__ void phase_kmat(CP P) {
;     const float* Ktab = (const float*)(P->ws + OFF_KTAB); bf16_t* KG = (bf16_t*)(P->ws + OFF_KG); const float* dsk = P->in[16];
;     for (int idx = obid() * NTHR + otid(); idx < 32 * 1024 * 512; idx += gridDim.x * NTHR) {
;         const int kp = idx & 511, row = (idx >> 9) & 1023, g = idx >> 19, t = row >> 4, p = row & 15, k = kp * 2, s = k >> 4, pp = k & 15;
;         float v0 = 0.f, v1 = 0.f;
;         if (s <= t) { const float* b = Ktab + ((size_t)((g * 2 + 0) * 64 + (t - s))) * 256 + p * 16 + pp; v0 += b[0]; v1 += b[1]; }
;         if (s >= t) { const float* b = Ktab + ((size_t)((g * 2 + 1) * 64 + (s - t))) * 256 + p * 16 + pp; v0 += b[0]; v1 += b[1]; }
;         if (s == t) { const float dv = dsk[g * 16 + p]; if (pp == p) v0 += dv; if (pp + 1 == p) v1 += dv; }
;         *(unsigned*)(KG + ((size_t)(g * 1024 + row)) * 1280 + k) = pack2(v0, v1);
;     }
; }
.LBB0_555:
	v_readlane_b32 s10, v254, 54
	v_readlane_b32 s11, v254, 55
	s_andn2_b64 vcc, exec, s[10:11]
	s_cbranch_vccnz .LBB0_566
	s_mov_b32 s10, s2
	v_mov_b32_e32 v0, v191
	s_mov_b64 s[20:21], exec
	v_readlane_b32 s16, v255, 2
	v_readlane_b32 s17, v255, 3
	v_readlane_b32 s26, v255, 6
	v_readlane_b32 s27, v255, 7
	s_load_dwordx2 s[12:13], s[0:1], 0x80
	v_mov_b32_e32 v185, v184
	v_mov_b32_e32 v62, 0
	v_lshrrev_b32_e32 v1, 3, v0
	v_lshlrev_b32_e32 v2, 1, v0
	v_and_b32_e32 v2, 14, v2
	v_or_b32_e32 v43, 1, v2
	s_and_b32 s24, s10, 15
	s_lshr_b32 s25, s10, 4
	s_lshl_b32 s11, s24, 6
	v_lshlrev_b32_e32 v3, 2, v2
	v_add_u32_e32 v3, s11, v3
	s_mulk_i32 s10, 0xa00
	v_lshl_add_u32 v44, v0, 2, s10
	s_add_i32 s11, s25, 0
	v_sub_u32_e32 v40, s11, v1
	v_max_i32_e32 v41, 0, v40
	v_sub_u32_e32 v42, 0, v40
	v_max_i32_e32 v42, 0, v42
	v_lshl_add_u32 v4, v41, 10, v3
	v_lshl_add_u32 v8, v42, 10, v3
	v_add_u32_e32 v8, 0x10000, v8
	v_cmp_le_i32_e32 vcc, 0, v40
	v_cmp_eq_u32_e64 s[22:23], 0, v40
	s_nop 1
	v_cndmask_b32_e64 v12, 0, 1.0, vcc
	v_cmp_ge_i32_e32 vcc, 0, v40
	s_nop 1
	v_cndmask_b32_e64 v13, 0, 1.0, vcc
	v_cmp_eq_u32_e32 vcc, s24, v2
	s_and_b64 vcc, vcc, s[22:23]
	v_cndmask_b32_e64 v20, 0, 1.0, vcc
	v_cmp_eq_u32_e32 vcc, s24, v43
	s_and_b64 vcc, vcc, s[22:23]
	v_cndmask_b32_e64 v21, 0, 1.0, vcc
	v_mov_b32_e32 v28, v44
	s_add_i32 s11, s25, 16
	v_sub_u32_e32 v40, s11, v1
	v_max_i32_e32 v41, 0, v40
	v_sub_u32_e32 v42, 0, v40
	v_max_i32_e32 v42, 0, v42
	v_lshl_add_u32 v5, v41, 10, v3
	v_lshl_add_u32 v9, v42, 10, v3
	v_add_u32_e32 v9, 0x10000, v9
	v_cmp_le_i32_e32 vcc, 0, v40
	v_cmp_eq_u32_e64 s[22:23], 0, v40
	s_nop 1
	v_cndmask_b32_e64 v14, 0, 1.0, vcc
	v_cmp_ge_i32_e32 vcc, 0, v40
	s_nop 1
	v_cndmask_b32_e64 v15, 0, 1.0, vcc
	v_cmp_eq_u32_e32 vcc, s24, v2
	s_and_b64 vcc, vcc, s[22:23]
	v_cndmask_b32_e64 v22, 0, 1.0, vcc
	v_cmp_eq_u32_e32 vcc, s24, v43
	s_and_b64 vcc, vcc, s[22:23]
	v_cndmask_b32_e64 v23, 0, 1.0, vcc
	v_add_u32_e32 v29, 0xa0000, v44
	s_add_i32 s11, s25, 32
	v_sub_u32_e32 v40, s11, v1
	v_max_i32_e32 v41, 0, v40
	v_sub_u32_e32 v42, 0, v40
	v_max_i32_e32 v42, 0, v42
	v_lshl_add_u32 v6, v41, 10, v3
	v_lshl_add_u32 v10, v42, 10, v3
	v_add_u32_e32 v10, 0x10000, v10
	v_cmp_le_i32_e32 vcc, 0, v40
	v_cmp_eq_u32_e64 s[22:23], 0, v40
	s_nop 1
	v_cndmask_b32_e64 v16, 0, 1.0, vcc
	v_cmp_ge_i32_e32 vcc, 0, v40
	s_nop 1
	v_cndmask_b32_e64 v17, 0, 1.0, vcc
	v_cmp_eq_u32_e32 vcc, s24, v2
	s_and_b64 vcc, vcc, s[22:23]
	v_cndmask_b32_e64 v24, 0, 1.0, vcc
	v_cmp_eq_u32_e32 vcc, s24, v43
	s_and_b64 vcc, vcc, s[22:23]
	v_cndmask_b32_e64 v25, 0, 1.0, vcc
	v_add_u32_e32 v30, 0x140000, v44
	s_add_i32 s11, s25, 48
	v_sub_u32_e32 v40, s11, v1
	v_max_i32_e32 v41, 0, v40
	v_sub_u32_e32 v42, 0, v40
	v_max_i32_e32 v42, 0, v42
	v_lshl_add_u32 v7, v41, 10, v3
	v_lshl_add_u32 v11, v42, 10, v3
	v_add_u32_e32 v11, 0x10000, v11
	v_cmp_le_i32_e32 vcc, 0, v40
	v_cmp_eq_u32_e64 s[22:23], 0, v40
	s_nop 1
	v_cndmask_b32_e64 v18, 0, 1.0, vcc
	v_cmp_ge_i32_e32 vcc, 0, v40
	s_nop 1
	v_cndmask_b32_e64 v19, 0, 1.0, vcc
	v_cmp_eq_u32_e32 vcc, s24, v2
	s_and_b64 vcc, vcc, s[22:23]
	v_cndmask_b32_e64 v26, 0, 1.0, vcc
	v_cmp_eq_u32_e32 vcc, s24, v43
	s_and_b64 vcc, vcc, s[22:23]
	v_cndmask_b32_e64 v27, 0, 1.0, vcc
	v_add_u32_e32 v31, 0x1e0000, v44
	s_waitcnt lgkmcnt(0)
	s_lshl_b32 s11, s24, 2
	s_add_u32 s12, s12, s11
	s_addc_u32 s13, s13, 0
	global_load_dword v60, v62, s[12:13]
	global_load_dwordx2 v[32:33], v4, s[16:17]
	global_load_dwordx2 v[34:35], v8, s[16:17]
	global_load_dwordx2 v[36:37], v5, s[16:17]
	global_load_dwordx2 v[38:39], v9, s[16:17]
	global_load_dwordx2 v[40:41], v6, s[16:17]
	global_load_dwordx2 v[42:43], v10, s[16:17]
	global_load_dwordx2 v[44:45], v7, s[16:17]
	global_load_dwordx2 v[46:47], v11, s[16:17]
	s_mov_b32 s11, 32
	s_waitcnt vmcnt(0)
	s_branch .Lkm_body
.Lkm_loop:
	s_waitcnt vmcnt(4)
.Lkm_body:
	v_pk_mul_f32 v[48:49], v[32:33], v[12:13] op_sel_hi:[1,0]
	v_pk_mul_f32 v[50:51], v[36:37], v[14:15] op_sel_hi:[1,0]
	v_pk_mul_f32 v[52:53], v[40:41], v[16:17] op_sel_hi:[1,0]
	v_pk_mul_f32 v[54:55], v[44:45], v[18:19] op_sel_hi:[1,0]
	v_pk_fma_f32 v[48:49], v[34:35], v[12:13], v[48:49] op_sel:[0,1,0] op_sel_hi:[1,1,1]
	v_pk_fma_f32 v[50:51], v[38:39], v[14:15], v[50:51] op_sel:[0,1,0] op_sel_hi:[1,1,1]
	v_pk_fma_f32 v[52:53], v[42:43], v[16:17], v[52:53] op_sel:[0,1,0] op_sel_hi:[1,1,1]
	v_pk_fma_f32 v[54:55], v[46:47], v[18:19], v[54:55] op_sel:[0,1,0] op_sel_hi:[1,1,1]
	v_pk_fma_f32 v[48:49], v[20:21], v[60:61], v[48:49] op_sel_hi:[1,0,1]
	v_pk_fma_f32 v[50:51], v[22:23], v[60:61], v[50:51] op_sel_hi:[1,0,1]
	v_pk_fma_f32 v[52:53], v[24:25], v[60:61], v[52:53] op_sel_hi:[1,0,1]
	v_pk_fma_f32 v[54:55], v[26:27], v[60:61], v[54:55] op_sel_hi:[1,0,1]
	v_cvt_pk_bf16_f32 v56, v48, v49
	v_cvt_pk_bf16_f32 v57, v50, v51
	v_cvt_pk_bf16_f32 v58, v52, v53
	v_cvt_pk_bf16_f32 v59, v54, v55
	s_add_u32 s16, s16, 0x20000
	s_addc_u32 s17, s17, 0
	s_add_u32 s12, s12, 64
	s_addc_u32 s13, s13, 0
	s_add_i32 s11, s11, -1
	s_cmp_lg_u32 s11, 0
	s_cbranch_scc0 .Lkm_st
	global_load_dword v60, v62, s[12:13]
	global_load_dwordx2 v[32:33], v4, s[16:17]
	global_load_dwordx2 v[34:35], v8, s[16:17]
	global_load_dwordx2 v[36:37], v5, s[16:17]
	global_load_dwordx2 v[38:39], v9, s[16:17]
	global_load_dwordx2 v[40:41], v6, s[16:17]
	global_load_dwordx2 v[42:43], v10, s[16:17]
	global_load_dwordx2 v[44:45], v7, s[16:17]
	global_load_dwordx2 v[46:47], v11, s[16:17]
.Lkm_st:
	global_store_dword v28, v56, s[26:27]
	global_store_dword v29, v57, s[26:27]
	global_store_dword v30, v58, s[26:27]
	global_store_dword v31, v59, s[26:27]
	s_add_u32 s26, s26, 0x280000
	s_addc_u32 s27, s27, 0
	s_cmp_lg_u32 s11, 0
	s_cbranch_scc1 .Lkm_loop
